# 64-bit accumulator zeroing in GEMM tile loops + first grid sync uses the XCD barrier instead of cooperative-groups sync
# baseline (speedup 1.0000x reference)
; template <class Epi, class Sched, bool ALIGN_EPI = false, bool SP2 = false>
; __device__ __forceinline__ void gemm_phase(PG8_LAS unsigned char* lds, const Gemm g, const Sched& S, const Epi& E) {
;     ...
; #pragma unroll
;         for (int a = 0; a < 2; ++a)
; #pragma unroll
;             for (int b = 0; b < 2; ++b)
; #pragma unroll
;                 for (int m = 0; m < 4; ++m)
; #pragma unroll
;                     for (int n = 0; n < 2; ++n) acc[a][b][m][n] = (f32x4){0.f, 0.f, 0.f, 0.f};
;         cur = nxt; cA = nA; cB = nB; ++ui;
.LBB0_59:
	s_add_u32 vcc_lo, s74, 0x80
	s_addc_u32 vcc_hi, s75, 0
	s_add_u32 s74, s72, 0x100
	v_mov_b64_e32 v[2:3], 0
	s_addc_u32 s75, s73, 0
	s_mov_b32 s72, 0
	v_mov_b64_e32 v[4:5], 0
	v_mov_b64_e32 v[6:7], 0
	v_mov_b64_e32 v[8:9], 0
	v_mov_b64_e32 v[10:11], 0
	v_mov_b64_e32 v[12:13], 0
	v_mov_b64_e32 v[14:15], 0
	v_mov_b64_e32 v[16:17], 0
	v_mov_b64_e32 v[18:19], 0
	v_mov_b64_e32 v[20:21], 0
	v_mov_b64_e32 v[22:23], 0
	v_mov_b64_e32 v[24:25], 0
	v_mov_b64_e32 v[26:27], 0
	v_mov_b64_e32 v[28:29], 0
	v_mov_b64_e32 v[30:31], 0
	v_mov_b64_e32 v[32:33], 0
	v_mov_b64_e32 v[34:35], 0
	v_mov_b64_e32 v[36:37], 0
	v_mov_b64_e32 v[38:39], 0
	v_mov_b64_e32 v[40:41], 0
	v_mov_b64_e32 v[42:43], 0
	v_mov_b64_e32 v[44:45], 0
	v_mov_b64_e32 v[46:47], 0
	v_mov_b64_e32 v[48:49], 0
	v_mov_b64_e32 v[50:51], 0
	v_mov_b64_e32 v[52:53], 0
	v_mov_b64_e32 v[54:55], 0
	v_mov_b64_e32 v[56:57], 0
	v_mov_b64_e32 v[58:59], 0
	v_mov_b64_e32 v[60:61], 0
	v_mov_b64_e32 v[62:63], 0
	v_mov_b64_e32 v[64:65], 0
	v_mov_b64_e32 v[66:67], 0
	v_mov_b64_e32 v[68:69], 0
	v_mov_b64_e32 v[70:71], 0
	v_mov_b64_e32 v[72:73], 0
	v_mov_b64_e32 v[74:75], 0
	v_mov_b64_e32 v[76:77], 0
	v_mov_b64_e32 v[78:79], 0
	v_mov_b64_e32 v[80:81], 0
	v_mov_b64_e32 v[82:83], 0
	v_mov_b64_e32 v[84:85], 0
	v_mov_b64_e32 v[86:87], 0
	v_mov_b64_e32 v[88:89], 0
	v_mov_b64_e32 v[90:91], 0
	v_mov_b64_e32 v[92:93], 0
	v_mov_b64_e32 v[94:95], 0
	v_mov_b64_e32 v[96:97], 0
	v_mov_b64_e32 v[98:99], 0
	v_mov_b64_e32 v[100:101], 0
	v_mov_b64_e32 v[102:103], 0
	v_mov_b64_e32 v[104:105], 0
	v_mov_b64_e32 v[106:107], 0
	v_mov_b64_e32 v[108:109], 0
	v_mov_b64_e32 v[110:111], 0
	v_mov_b64_e32 v[112:113], 0
	v_mov_b64_e32 v[114:115], 0
	v_mov_b64_e32 v[116:117], 0
	v_mov_b64_e32 v[118:119], 0
	v_mov_b64_e32 v[120:121], 0
	v_mov_b64_e32 v[122:123], 0
	v_mov_b64_e32 v[124:125], 0
	v_mov_b64_e32 v[126:127], 0
	v_mov_b64_e32 v[128:129], 0

; template <class Epi, class Sched, bool ALIGN_EPI = false, bool SP2 = false>
; __device__ __forceinline__ void gemm_phase(PG8_LAS unsigned char* lds, const Gemm g, const Sched& S, const Epi& E) {
;     ...
; #pragma unroll
;         for (int a = 0; a < 2; ++a)
; #pragma unroll
;             for (int b = 0; b < 2; ++b)
; #pragma unroll
;                 for (int m = 0; m < 4; ++m)
; #pragma unroll
;                     for (int n = 0; n < 2; ++n) acc[a][b][m][n] = (f32x4){0.f, 0.f, 0.f, 0.f};
;         cur = nxt; cA = nA; cB = nB; ++ui;
.LBB0_480:
	s_ashr_i32 s17, s16, 31
	s_lshl_b64 s[18:19], s[16:17], 19
	s_add_u32 s20, s48, s18
	s_addc_u32 s21, s49, s19
	s_and_b64 s[18:19], s[6:7], exec
	s_cselect_b32 s4, s21, s39
	s_cselect_b32 s17, s20, s38
	s_ashr_i32 s15, s14, 31
	s_lshl_b64 s[18:19], s[14:15], 19
	s_add_u32 s34, s66, s18
	s_addc_u32 s35, s67, s19
	s_and_b64 s[18:19], s[6:7], exec
	s_cselect_b32 s15, s35, s43
	s_cselect_b32 s18, s34, s42
	s_add_u32 s38, s38, 0x40080
	s_addc_u32 s39, s39, 0
	s_add_u32 s19, s42, 0x100
	v_mov_b64_e32 v[2:3], 0
	s_addc_u32 s23, s43, 0
	s_mov_b32 s30, -2
	v_mov_b64_e32 v[4:5], 0
	v_mov_b64_e32 v[6:7], 0
	v_mov_b64_e32 v[8:9], 0
	v_mov_b64_e32 v[10:11], 0
	v_mov_b64_e32 v[12:13], 0
	v_mov_b64_e32 v[14:15], 0
	v_mov_b64_e32 v[16:17], 0
	v_mov_b64_e32 v[18:19], 0
	v_mov_b64_e32 v[20:21], 0
	v_mov_b64_e32 v[22:23], 0
	v_mov_b64_e32 v[24:25], 0
	v_mov_b64_e32 v[26:27], 0
	v_mov_b64_e32 v[28:29], 0
	v_mov_b64_e32 v[30:31], 0
	v_mov_b64_e32 v[32:33], 0
	v_mov_b64_e32 v[34:35], 0
	v_mov_b64_e32 v[36:37], 0
	v_mov_b64_e32 v[38:39], 0
	v_mov_b64_e32 v[40:41], 0
	v_mov_b64_e32 v[42:43], 0
	v_mov_b64_e32 v[44:45], 0
	v_mov_b64_e32 v[46:47], 0
	v_mov_b64_e32 v[48:49], 0
	v_mov_b64_e32 v[66:67], 0
	v_mov_b64_e32 v[68:69], 0
	v_mov_b64_e32 v[70:71], 0
	v_mov_b64_e32 v[72:73], 0
	v_mov_b64_e32 v[74:75], 0
	v_mov_b64_e32 v[76:77], 0
	v_mov_b64_e32 v[78:79], 0
	v_mov_b64_e32 v[80:81], 0
	v_mov_b64_e32 v[82:83], 0
	v_mov_b64_e32 v[84:85], 0
	v_mov_b64_e32 v[86:87], 0
	v_mov_b64_e32 v[88:89], 0
	v_mov_b64_e32 v[90:91], 0
	v_mov_b64_e32 v[92:93], 0
	v_mov_b64_e32 v[94:95], 0
	v_mov_b64_e32 v[96:97], 0
	v_mov_b64_e32 v[98:99], 0
	v_mov_b64_e32 v[100:101], 0
	v_mov_b64_e32 v[102:103], 0
	v_mov_b64_e32 v[104:105], 0
	v_mov_b64_e32 v[106:107], 0
	v_mov_b64_e32 v[108:109], 0
	v_mov_b64_e32 v[110:111], 0
	v_mov_b64_e32 v[112:113], 0
	v_mov_b64_e32 v[114:115], 0
	v_mov_b64_e32 v[116:117], 0
	v_mov_b64_e32 v[118:119], 0
	v_mov_b64_e32 v[120:121], 0
	v_mov_b64_e32 v[122:123], 0
	v_mov_b64_e32 v[124:125], 0
	v_mov_b64_e32 v[126:127], 0
	v_mov_b64_e32 v[128:129], 0
	v_mov_b64_e32 v[130:131], 0
	v_mov_b64_e32 v[132:133], 0
	v_mov_b64_e32 v[134:135], 0
	v_mov_b64_e32 v[136:137], 0
	v_mov_b64_e32 v[138:139], 0
	v_mov_b64_e32 v[140:141], 0
	v_mov_b64_e32 v[142:143], 0
	v_mov_b64_e32 v[144:145], 0
	s_waitcnt vmcnt(0)

; template <class Epi, class Sched, bool ALIGN_EPI = false, bool SP2 = false>
; __device__ __forceinline__ void gemm_phase(PG8_LAS unsigned char* lds, const Gemm g, const Sched& S, const Epi& E) {
;     ...
; #pragma unroll
;         for (int a = 0; a < 2; ++a)
; #pragma unroll
;             for (int b = 0; b < 2; ++b)
; #pragma unroll
;                 for (int m = 0; m < 4; ++m)
; #pragma unroll
;                     for (int n = 0; n < 2; ++n) acc[a][b][m][n] = (f32x4){0.f, 0.f, 0.f, 0.f};
;         cur = nxt; cA = nA; cB = nB; ++ui;
.LBB0_507:
	s_ashr_i32 s15, s14, 31
	s_lshl_b64 s[16:17], s[14:15], 19
	s_add_u32 s16, s24, s16
	s_addc_u32 s17, s25, s17
	s_and_b64 s[18:19], s[6:7], exec
	s_cselect_b32 s4, s17, s37
	s_cselect_b32 s15, s16, s36
	s_ashr_i32 s13, s12, 31
	s_lshl_b64 s[18:19], s[12:13], 19
	s_add_u32 s20, s0, s18
	s_addc_u32 s21, s44, s19
	s_and_b64 s[18:19], s[6:7], exec
	s_cselect_b32 s13, s21, s39
	s_cselect_b32 s18, s20, s38
	s_add_u32 s36, s36, 0x40080
	s_addc_u32 s37, s37, 0
	s_add_u32 s19, s38, 0x100
	v_mov_b64_e32 v[2:3], 0
	s_addc_u32 s23, s39, 0
	s_mov_b32 s33, -2
	v_mov_b64_e32 v[4:5], 0
	v_mov_b64_e32 v[6:7], 0
	v_mov_b64_e32 v[8:9], 0
	v_mov_b64_e32 v[10:11], 0
	v_mov_b64_e32 v[12:13], 0
	v_mov_b64_e32 v[14:15], 0
	v_mov_b64_e32 v[16:17], 0
	v_mov_b64_e32 v[18:19], 0
	v_mov_b64_e32 v[20:21], 0
	v_mov_b64_e32 v[22:23], 0
	v_mov_b64_e32 v[24:25], 0
	v_mov_b64_e32 v[26:27], 0
	v_mov_b64_e32 v[28:29], 0
	v_mov_b64_e32 v[30:31], 0
	v_mov_b64_e32 v[32:33], 0
	v_mov_b64_e32 v[34:35], 0
	v_mov_b64_e32 v[36:37], 0
	v_mov_b64_e32 v[38:39], 0
	v_mov_b64_e32 v[40:41], 0
	v_mov_b64_e32 v[42:43], 0
	v_mov_b64_e32 v[44:45], 0
	v_mov_b64_e32 v[46:47], 0
	v_mov_b64_e32 v[48:49], 0
	v_mov_b64_e32 v[50:51], 0
	v_mov_b64_e32 v[52:53], 0
	v_mov_b64_e32 v[54:55], 0
	v_mov_b64_e32 v[56:57], 0
	v_mov_b64_e32 v[58:59], 0
	v_mov_b64_e32 v[60:61], 0
	v_mov_b64_e32 v[62:63], 0
	v_mov_b64_e32 v[64:65], 0
	v_mov_b64_e32 v[66:67], 0
	v_mov_b64_e32 v[68:69], 0
	v_mov_b64_e32 v[70:71], 0
	v_mov_b64_e32 v[72:73], 0
	v_mov_b64_e32 v[74:75], 0
	v_mov_b64_e32 v[76:77], 0
	v_mov_b64_e32 v[78:79], 0
	v_mov_b64_e32 v[80:81], 0
	v_mov_b64_e32 v[82:83], 0
	v_mov_b64_e32 v[84:85], 0
	v_mov_b64_e32 v[86:87], 0
	v_mov_b64_e32 v[88:89], 0
	v_mov_b64_e32 v[90:91], 0
	v_mov_b64_e32 v[92:93], 0
	v_mov_b64_e32 v[94:95], 0
	v_mov_b64_e32 v[96:97], 0
	v_mov_b64_e32 v[98:99], 0
	v_mov_b64_e32 v[100:101], 0
	v_mov_b64_e32 v[102:103], 0
	v_mov_b64_e32 v[104:105], 0
	v_mov_b64_e32 v[106:107], 0
	v_mov_b64_e32 v[108:109], 0
	v_mov_b64_e32 v[110:111], 0
	v_mov_b64_e32 v[112:113], 0
	v_mov_b64_e32 v[114:115], 0
	v_mov_b64_e32 v[116:117], 0
	v_mov_b64_e32 v[118:119], 0
	v_mov_b64_e32 v[120:121], 0
	v_mov_b64_e32 v[122:123], 0
	v_mov_b64_e32 v[124:125], 0
	v_mov_b64_e32 v[126:127], 0
	v_mov_b64_e32 v[128:129], 0

; #define LAS __attribute__((address_space(3)))
; __device__ __forceinline__ unsigned xb_ld(unsigned* p)              { return __hip_atomic_load(p, __ATOMIC_RELAXED, __HIP_MEMORY_SCOPE_AGENT); }
; __device__ __forceinline__ unsigned xb_xcc_id() { return (unsigned)__builtin_amdgcn_s_getreg((3 << 11) | 20) & 0xFu; }
; __device__ __forceinline__ void xcd_barrier_complete(unsigned* bar, unsigned x, unsigned& nloc, unsigned& nx) {
;     const unsigned G = gridDim.x * gridDim.y * gridDim.z;
;     unsigned sum, cnt, mine, sp = 0u;
;     for (;;) {
;         sum = 0u; cnt = 0u; mine = 0u;
; #pragma unroll
;         for (unsigned j = 0; j < 16; ++j) { const unsigned c = xb_ld(&bar[XB_XCNT(j)]); sum += c; cnt += (c > 0u) ? 1u : 0u; mine = (j == x) ? c : mine; }
;         if (sum == G) break;
;         __builtin_amdgcn_s_sleep(1);
;         if ((++sp & 255u) == 0u) { if (xb_ld(&bar[XB_TMO])) break; if (sp > XB_SPIN_CAP) { atomicAdd(&bar[XB_TMO], 1u); break; } }
;     }
;     nloc = mine > 0u ? mine : 1u; nx = cnt > 0u ? cnt : 1u;
; }
; __device__ __forceinline__ void xcd_barrier(const XcdBarrier& b) {
;     asm volatile("s_waitcnt vmcnt(0)" ::: "memory");
;     __syncthreads();
;     if (threadIdx.x == 0) {
;         unsigned* bar = b.bar;
;         __builtin_amdgcn_s_waitcnt(0);
;         unsigned nloc = b.st[0], nx = b.st[1];
;         if (nloc == 0u) { xcd_barrier_complete(bar, b.x, nloc, nx); b.st[0] = nloc; b.st[1] = nx; }
; __global__ void __launch_bounds__(NTHREADS, 2) mega(Args a_) {
;     ...
;         if (ph + 1 < ph_hi) { if (ph == ph_lo) cg::this_grid().sync(); else { XcdBarrier xbar; xbar.bar = (unsigned*)(a->ws + WS_CTL_BAR); xbar.x = xb_xcc_id(); xbar.st = (volatile LAS unsigned*)(lds + 131072 + 64); xcd_barrier(xbar); } }
.LBB0_517:
	s_cmp_lg_u32 s22, s86
	s_mov_b64 s[6:7], -1
	s_getreg_b32 s0, hwreg(HW_REG_XCC_ID, 0, 4)
	s_waitcnt vmcnt(0)
	s_waitcnt vmcnt(0)
	s_barrier
	s_mov_b64 s[6:7], exec
	v_readlane_b32 s8, v255, 0
	v_readlane_b32 s9, v255, 1
	s_and_b64 s[8:9], s[6:7], s[8:9]
	s_mov_b64 exec, s[8:9]
	s_cbranch_execz .LBB0_570
	v_readlane_b32 s1, v255, 6
	s_waitcnt vmcnt(0) expcnt(0) lgkmcnt(0)
	s_and_b32 s0, s0, 15
	v_mov_b32_e32 v0, s1
	ds_read_b32 v3, v0
	v_readlane_b32 s1, v255, 7
	s_waitcnt lgkmcnt(0)
	v_cmp_ne_u32_e32 vcc, 0, v3
	v_mov_b32_e32 v0, s1
	ds_read_b32 v2, v0
	s_cbranch_vccnz .LBB0_534
	s_load_dwordx2 s[12:13], s[90:91], 0x0
	s_load_dword s1, s[90:91], 0x8
	s_add_u32 s8, s26, 0x4200
	s_addc_u32 s9, s27, 0
	s_add_u32 s10, s26, 0x4400
	s_addc_u32 s11, s27, 0
	s_waitcnt lgkmcnt(0)
	s_mul_i32 s4, s13, s12
	s_add_u32 s12, s26, 0x4500
	s_addc_u32 s13, s27, 0
	s_add_u32 s14, s26, 0x4600
	s_addc_u32 s15, s27, 0
	s_add_u32 s16, s26, 0x4700
	s_addc_u32 s17, s27, 0
	s_add_u32 s20, s26, 0x4800
	s_addc_u32 s21, s27, 0
	s_add_u32 s24, s26, 0x4900
	s_addc_u32 s25, s27, 0
	s_add_u32 s34, s26, 0x4a00
	s_addc_u32 s35, s27, 0
	s_add_u32 s36, s26, 0x4b00
	s_addc_u32 s37, s27, 0
	s_add_u32 s38, s26, 0x4c00
	s_addc_u32 s39, s27, 0
	s_add_u32 s42, s26, 0x4d00
	s_addc_u32 s43, s27, 0
	s_add_u32 s44, s26, 0x4e00
	s_addc_u32 s45, s27, 0
	s_add_u32 s46, s26, 0x4f00
	s_addc_u32 s47, s27, 0
	s_add_u32 s66, s26, 0x5000
	s_addc_u32 s67, s27, 0
	s_add_u32 s68, s26, 0x5100
	s_addc_u32 s69, s27, 0
	s_add_u32 s70, s26, 0x5200
	s_addc_u32 s71, s27, 0
	s_add_u32 s72, s26, 0x5300
	s_mul_i32 s1, s4, s1
	s_addc_u32 s73, s27, 0
	s_mov_b32 s4, 1
	s_branch .LBB0_522
